# co-resident block stagger: blocks >= 256 enter gemm_in / ffn_in half a k-step late (s_sleep 41); otherwise v111
# baseline (speedup 1.0000x reference)
.LBB0_209:
	s_not_b32 s2, s5
	s_add_i32 s2, s8, s2
	s_add_i32 s2, s2, s17
	s_ashr_i32 s3, s2, 31
	s_abs_i32 s2, s2
	s_mul_hi_u32 s5, s2, s72
	s_mul_i32 s8, s5, s4
	s_sub_i32 s2, s2, s8
	s_xor_b32 s3, s3, s16
	s_add_i32 s8, s5, 1
	s_sub_i32 s9, s2, s4
	s_cmp_ge_u32 s2, s4
	s_cselect_b32 s5, s8, s5
	s_cselect_b32 s2, s9, s2
	s_add_i32 s8, s5, 1
	s_cmp_ge_u32 s2, s4
	s_cselect_b32 s2, s8, s5
	s_xor_b32 s2, s2, s3
	s_sub_i32 s2, s2, s3
	s_add_i32 s3, s15, s24
	s_not_b32 s4, s23
	s_add_i32 s4, s4, s3
	s_ashr_i32 s3, s4, 31
	s_abs_i32 s4, s4
	s_mul_i32 s1, s4, s1
	s_mul_hi_u32 s0, s4, s0
	s_add_i32 s0, s0, s1
	s_mul_i32 s1, s0, s12
	s_sub_i32 s1, s4, s1
	s_xor_b32 s3, s3, s13
	s_add_i32 s4, s0, 1
	s_sub_i32 s5, s1, s12
	s_cmp_ge_u32 s1, s12
	s_cselect_b32 s0, s4, s0
	s_cselect_b32 s1, s5, s1
	s_add_i32 s4, s0, 1
	s_cmp_ge_u32 s1, s12
	s_cselect_b32 s0, s4, s0
	s_xor_b32 s0, s0, s3
	s_sub_i32 s3, s0, s3
	s_cmp_lt_i32 s22, 0
	s_cselect_b64 s[8:9], -1, 0
	s_and_b64 s[0:1], s[8:9], exec
	s_cselect_b32 s26, s3, s2
	s_not_b32 s0, s14
	s_lshr_b32 s0, s0, 31
	s_add_i32 s26, s26, s0
	s_cmp_lt_i32 s26, 1
	s_cbranch_scc1 .LBB0_476
	s_lshr_b32 s27, s10, 3
	s_cmp_lt_i32 s14, 0
	s_mul_hi_u32 s0, s14, 0x3521cfb3
	s_cselect_b64 s[10:11], -1, 0
	s_sub_i32 s2, s14, s0
	s_lshr_b32 s2, s2, 1
	s_add_i32 s2, s2, s0
	s_lshr_b32 s0, s2, 5
	s_add_i32 s28, s0, 0x80
	s_mul_i32 s0, s0, 53
	v_and_b32_e32 v2, 15, v0
	s_sub_i32 s29, s14, s0
	v_ashrrev_i32_e32 v3, 1, v0
	s_movk_i32 s0, 0xffc0
	v_and_or_b32 v87, v3, s0, v2
	v_lshrrev_b32_e32 v2, 2, v0
	v_and_b32_e32 v2, 12, v2
	v_and_or_b32 v86, v0, 64, v2
	v_and_b32_e32 v0, 64, v0
	v_cmp_ne_u32_e64 s[40:41], 0, v0
	v_or_b32_e32 v0, 16, v86
	v_cmp_gt_u32_e64 s[44:45], 40, v0
	v_or_b32_e32 v0, 32, v86
	v_cmp_gt_u32_e64 s[4:5], 40, v0
	v_cvt_f32_u32_e32 v0, s25
	v_readlane_b32 s2, v249, 52
	s_load_dwordx2 s[12:13], s[6:7], 0x138
	s_load_dwordx2 s[14:15], s[6:7], 0xe0
	s_lshl_b32 s0, s2, 8
	v_rcp_iflag_f32_e32 v0, v0
	s_or_b32 s30, s0, 0xffffc000
	s_sub_i32 s0, 0, s25
	s_mov_b32 s18, s2
	v_mul_f32_e32 v0, 0x4f7ffffe, v0
	v_cvt_u32_f32_e32 v0, v0
	v_readlane_b32 s3, v249, 53
	s_mul_i32 s72, s2, 0xc00
	s_lshl_b32 s31, s2, 14
	v_readfirstlane_b32 s16, v0
	s_mul_i32 s0, s0, s16
	s_mul_hi_u32 s0, s16, s0
	s_lshl_b32 s2, s2, 6
	s_add_i32 s33, s16, s0
	s_mul_i32 s16, s18, 0xd40000
	s_mov_b32 s3, s73
	s_mul_hi_u32 s0, s18, 0xd40000
	s_waitcnt lgkmcnt(0)
	s_add_u32 s34, s14, s16
	s_mov_b32 s1, 0
	v_or_b32_e32 v104, 0xfffff180, v86
	v_cmp_gt_u32_e64 s[42:43], 40, v86
	s_addc_u32 s35, s15, s0
	s_lshl_b64 s[16:17], s[72:73], 2
	s_lshl_b64 s[18:19], s[2:3], 2
	v_lshlrev_b32_e32 v105, 2, v2
	s_mov_b32 s32, 0
	v_readlane_b32 s2, v249, 1
	s_nop 0
	s_cmpk_lg_u32 s2, 0x200
	s_cbranch_scc1 .LBB0_212
	v_readlane_b32 s2, v249, 0
	s_nop 0
	s_cmp_lt_u32 s2, 0x100
	s_cbranch_scc1 .Lg2_nostag
	s_sleep 41
.Lg2_nostag:
	s_mov_b32 s48, 0
	v_readlane_b32 s2, v249, 0
	s_nop 0
	s_and_b32 s3, s2, 7
	s_lshr_b32 s2, s2, 3
	s_cmp_lt_u32 s2, 40
	s_cselect_b32 s38, 7, 6
	s_cmp_lt_u32 s48, s38
	s_cbranch_scc0 .Lg2_c0_extra
	s_lshl_b32 s20, s48, 6
	s_add_i32 s20, s20, s2
	s_cmp_ge_u32 s20, 0xd4
	s_cselect_b32 s21, 1, 0
	s_mul_i32 s0, s21, 0xd4
	s_sub_i32 s20, s20, s0
	s_lshr_b32 s37, s20, 2
	s_and_b32 s20, s20, 3
	s_lshl_b32 s21, s21, 3
	s_add_i32 s20, s20, s21
	s_lshl_b32 s20, s20, 3
	s_add_i32 s0, s20, s3
	s_add_i32 s49, s0, 32
	s_branch .Lg2_c0_have

.Lg2_cb1:
	v_cvt_pk_bf16_f32 v164, v66, v67
	v_cvt_pk_bf16_f32 v165, v68, v69
	v_cvt_pk_bf16_f32 v166, v70, v71
	v_cvt_pk_bf16_f32 v167, v72, v73
	s_nop 1
	v_permlane16_swap_b32 v164, v166
	v_permlane16_swap_b32 v165, v167
	s_nop 1
	global_store_dwordx4 v156, v[164:167], s[96:97]
	v_cvt_pk_bf16_f32 v168, v82, v83
	v_cvt_pk_bf16_f32 v169, v84, v85
	v_cvt_pk_bf16_f32 v170, v88, v89
	v_cvt_pk_bf16_f32 v171, v90, v91
	s_nop 1
	v_permlane16_swap_b32 v168, v170
	v_permlane16_swap_b32 v169, v171
	s_nop 1
	global_store_dwordx4 v156, v[168:171], s[96:97] offset:64
	v_cvt_pk_bf16_f32 v164, v92, v93
	v_cvt_pk_bf16_f32 v165, v94, v95
	v_cvt_pk_bf16_f32 v166, v96, v97
	v_cvt_pk_bf16_f32 v167, v98, v99
	s_nop 1
	v_permlane16_swap_b32 v164, v166
	v_permlane16_swap_b32 v165, v167
	s_nop 1
	global_store_dwordx4 v157, v[164:167], s[96:97]
	v_cvt_pk_bf16_f32 v168, v100, v101
	v_cvt_pk_bf16_f32 v169, v102, v103
	v_cvt_pk_bf16_f32 v170, v106, v107
	v_cvt_pk_bf16_f32 v171, v108, v109
	s_nop 1
	v_permlane16_swap_b32 v168, v170
	v_permlane16_swap_b32 v169, v171
	s_nop 1
	global_store_dwordx4 v157, v[168:171], s[96:97] offset:64
	v_cvt_pk_bf16_f32 v164, v110, v111
	v_cvt_pk_bf16_f32 v165, v112, v113
	v_cvt_pk_bf16_f32 v166, v114, v115
	v_cvt_pk_bf16_f32 v167, v116, v117
	s_nop 1
	v_permlane16_swap_b32 v164, v166
	v_permlane16_swap_b32 v165, v167
	s_nop 1
	global_store_dwordx4 v158, v[164:167], s[96:97]
	v_cvt_pk_bf16_f32 v168, v118, v119
	v_cvt_pk_bf16_f32 v169, v120, v121
	v_cvt_pk_bf16_f32 v170, v122, v123
	v_cvt_pk_bf16_f32 v171, v124, v125
	s_nop 1
	v_permlane16_swap_b32 v168, v170
	v_permlane16_swap_b32 v169, v171
	s_nop 1
	global_store_dwordx4 v158, v[168:171], s[96:97] offset:64
	v_cvt_pk_bf16_f32 v164, v126, v127
	v_cvt_pk_bf16_f32 v165, v128, v129
	v_cvt_pk_bf16_f32 v166, v136, v137
	v_cvt_pk_bf16_f32 v167, v138, v139
	s_nop 1
	v_permlane16_swap_b32 v164, v166
	v_permlane16_swap_b32 v165, v167
	s_nop 1
	global_store_dwordx4 v159, v[164:167], s[96:97]
	v_cvt_pk_bf16_f32 v168, v140, v141
	v_cvt_pk_bf16_f32 v169, v142, v143
	v_cvt_pk_bf16_f32 v170, v144, v145
	v_cvt_pk_bf16_f32 v171, v146, v147
	s_nop 1
	v_permlane16_swap_b32 v168, v170
	v_permlane16_swap_b32 v169, v171
	s_nop 1
	global_store_dwordx4 v159, v[168:171], s[96:97] offset:64
	s_branch .Lg2_next
.Lg2_g8:
	s_branch .Lg2_2p
.Lg2_2p:
	s_mov_b32 s32, 1
	s_branch .LBB0_222

.LBB0_2352:
	v_and_b32_e32 v2, 15, v0
	v_ashrrev_i32_e32 v3, 1, v0
	s_movk_i32 s8, 0xffc0
	s_waitcnt vmcnt(2)
	v_and_or_b32 v74, v3, s8, v2
	v_lshrrev_b32_e32 v2, 1, v0
	v_lshrrev_b32_e32 v0, 2, v0
	s_and_b32 s17, s2, 7
	v_and_b32_e32 v0, 12, v0
	v_and_or_b32 v75, v2, 32, v0
	v_cvt_f32_ubyte0_e32 v0, s17
	v_rcp_iflag_f32_e32 v0, v0
	s_lshr_b32 s16, s2, 3
	s_cmp_lt_i32 s12, 0
	s_cselect_b64 s[2:3], -1, 0
	v_mul_f32_e32 v0, 0x4f7ffffe, v0
	v_cvt_u32_f32_e32 v0, v0
	s_sub_i32 s8, 0, s17
	s_load_dwordx2 s[4:5], s[0:1], 0x108
	s_load_dwordx2 s[6:7], s[0:1], 0x138
	v_readfirstlane_b32 s9, v0
	s_mul_i32 s8, s8, s9
	s_mul_hi_u32 s8, s9, s8
	s_add_i32 s18, s9, s8
	v_readlane_b32 s8, v249, 52
	v_readlane_b32 s9, v249, 53
	s_mov_b32 s10, s8
	s_mul_i32 s9, s10, 0xb00000
	s_mul_hi_u32 s8, s8, 0xb00000
	s_waitcnt lgkmcnt(0)
	s_add_u32 s19, s4, s9
	s_addc_u32 s20, s5, s8
	s_waitcnt vmcnt(0)
	s_mov_b32 s32, 0
	v_readlane_b32 s30, v249, 1
	s_nop 0
	s_cmpk_lg_u32 s30, 0x200
	s_cbranch_scc1 .LBB0_2354
	v_readlane_b32 s30, v249, 0
	s_nop 0
	s_cmp_lt_u32 s30, 0x100
	s_cbranch_scc1 .Lf2_nostag
	s_sleep 41
.Lf2_nostag:
	s_mov_b32 s48, 0
	v_readlane_b32 s30, v249, 0
	s_nop 0
	s_and_b32 s31, s30, 7
	s_lshr_b32 s30, s30, 3
	s_cmp_lt_u32 s30, 32
	s_cselect_b32 s35, 6, 5
	s_cmp_lt_u32 s48, s35
	s_cbranch_scc0 .Lf2_c0_extra
	s_lshl_b32 s33, s48, 6
	s_add_i32 s33, s33, s30
	s_cmp_ge_u32 s33, 0xb0
	s_cselect_b32 s34, 1, 0
	s_mul_i32 s8, s34, 0xb0
	s_sub_i32 s33, s33, s8
	s_lshr_b32 s21, s33, 2
	s_and_b32 s33, s33, 3
	s_lshl_b32 s34, s34, 3
	s_add_i32 s33, s33, s34
	s_lshl_b32 s33, s33, 3
	s_add_i32 s8, s33, s31
	s_add_i32 s49, s8, 32
	s_branch .Lf2_c0_have
